# cmp_stage2 on the f32 matrix cores: 4 rows per wave activated up front (row loads issued together), parked in LDS, one v_mfma_f32_4x4x1_16b_f32 per k (k-ordered f32 fma chain) instead of readlane+LDS+
# speedup vs baseline: 1.0080x; 1.0080x over previous
; #define LAS __attribute__((address_space(3)))
; __device__ __forceinline__ unsigned cvt_pk_bf16(float lo, float hi) { f32x2_t v = {lo, hi}; bf16x2_t b = __builtin_convertvector(v, bf16x2_t); return __builtin_bit_cast(unsigned, b); }
; __device__ __forceinline__ void cmp_stage2(const Ctx& C, int l) {
;     ...
;     LAS float* ws2 = (LAS float*)C.lds;
;     for (int e = C.tid; e < 256 * 64 / 4; e += NWAVES * 64) ((LAS f32x4*)ws2)[e] = ((const f32x4*)w2)[e];
;     __syncthreads();
;     const bf16_t* hid = (const bf16_t*)(C.ws + WS_CMPP) + (size_t)kv * 4096 * 256;
;     const float* cbias = (const float*)(C.ws + WS_CB) + l * 512 + kv * 256;
;     bf16_t* ko = (bf16_t*)(C.ws + WS_KCMP); bf16_t* vo = (bf16_t*)(C.ws + WS_VCMP);
;     const int d = C.lane;
;     for (int row = wi * NWAVES + C.wave; row < 4096; row += nwg2 * NWAVES) {
;         asm volatile("" ::: "memory");
;         const u32x2 hv = *((const u32x2*)(hid + (size_t)row * 256) + C.lane), hw = *((const u32x2*)(hid + (size_t)(row + 8192) * 256) + C.lane);
;         const f32x4 cbv = *((const f32x4*)cbias + C.lane);
;         const float h0 = gelu_tanh(bf_lo(hv.x) + bf_lo(hw.x) + cbv.x), h1 = gelu_tanh(bf_hi(hv.x) + bf_hi(hw.x) + cbv.y), h2 = gelu_tanh(bf_lo(hv.y) + bf_lo(hw.y) + cbv.z), h3 = gelu_tanh(bf_hi(hv.y) + bf_hi(hw.y) + cbv.w);
;         float acc = 0.f;
; #pragma unroll 4
;         for (int k = 0; k < 64; ++k) {
;             const float a0 = __int_as_float(__builtin_amdgcn_readlane(__float_as_int(h0), k)), a1 = __int_as_float(__builtin_amdgcn_readlane(__float_as_int(h1), k));
;             const float a2 = __int_as_float(__builtin_amdgcn_readlane(__float_as_int(h2), k)), a3 = __int_as_float(__builtin_amdgcn_readlane(__float_as_int(h3), k));
;             acc += a0 * ws2[(4 * k + 0) * 64 + d]; acc += a1 * ws2[(4 * k + 1) * 64 + d]; acc += a2 * ws2[(4 * k + 2) * 64 + d]; acc += a3 * ws2[(4 * k + 3) * 64 + d];
;         }
;         const int bg = row >> 10, n = row & 1023;
;         if (n == 1023) acc = 0.f;
;         const bf16_t o = (bf16_t)(cvt_pk_bf16(acc, 0.f) & 0xffffu);
;         if (kv == 0) ko[((size_t)((bg * 32 + (n >> 5)) * 4 + (d >> 4)) * 64 + pi32(n & 31) + 32 * ((d >> 3) & 1)) * 8 + (d & 7)] = o;
;         else vo[((size_t)((bg * 64 + (n >> 4)) * 2 + (d >> 5)) * 64 + (d & 31) + 32 * ((n >> 3) & 1)) * 8 + (n & 7)] = o;
.LBB0_583:
	s_or_b64 exec, exec, s[2:3]
	s_lshl_b32 s2, s12, 2
	s_and_b32 s2, s2, -8
	s_add_i32 s12, s2, s6
	s_cmpk_gt_i32 s12, 0xfff
	s_waitcnt lgkmcnt(0)
	s_barrier
	s_cbranch_scc1 .LBB0_592
	v_readlane_b32 s2, v254, 2
	s_sub_i32 s13, s2, s11
	v_readlane_b32 s2, v254, 45
	v_readlane_b32 s3, v254, 46
	s_lshl_b32 s6, s2, 9
	s_lshl_b64 s[2:3], s[6:7], 2
	s_add_u32 s2, s0, s2
	s_addc_u32 s3, s1, s3
	s_lshl_b32 s6, s11, 10
	s_add_u32 s2, s2, s6
	s_addc_u32 s3, s3, 0
	s_lshl_b32 s6, s11, 21
	s_add_u32 s8, s0, s6
	v_and_b32_e32 v10, 63, v0
	s_addc_u32 s9, s1, 0
	v_bfe_u32 v3, v0, 5, 1
	v_and_b32_e32 v2, 31, v0
	v_bfe_u32 v5, v0, 4, 2
	v_and_b32_e32 v0, 7, v0
	s_lshl_b32 s6, s13, 2
	s_lshr_b32 s10, s10, 5
	v_lshlrev_b32_e32 v0, 1, v0
	s_and_b32 s6, s6, -8
	s_and_b32 s10, s10, 14
	v_lshl_add_u64 v[6:7], s[0:1], 0, v[0:1]
	s_add_u32 s10, s0, s10
	v_lshlrev_b32_e32 v0, 3, v10
	s_addc_u32 s11, s1, 0
	v_lshl_add_u64 v[8:9], s[8:9], 0, v[0:1]
	v_lshlrev_b32_e32 v0, 4, v10
	v_lshlrev_b32_e32 v12, 2, v10
	s_mov_b64 s[16:17], 0x3d00000
	s_add_u32 s18, s10, 0x3d80000
	s_mov_b64 s[8:9], 0x1e400000
	v_lshl_add_u64 v[10:11], s[2:3], 0, v[0:1]
	s_mov_b64 s[2:3], 0x3900000
	v_and_b32_e32 v4, 32, v12
	v_lshl_add_u64 v[6:7], v[6:7], 0, s[16:17]
	s_addc_u32 s19, s11, 0
	v_lshl_add_u64 v[8:9], v[8:9], 0, s[8:9]
	v_lshl_add_u64 v[10:11], v[10:11], 0, s[2:3]
	v_add_u32_e32 v0, 0, v12
	s_mov_b32 s100, s12
	v_readlane_b32 s101, v254, 33
	s_nop 3
	s_lshl_b32 s101, s101, 2
	s_add_i32 s101, s101, 0x10000
	v_lshl_add_u32 v30, v0, 2, s101
	v_and_b32_e32 v31, 12, v0
	v_lshl_add_u32 v31, v31, 8, s101
	s_mov_b32 s2, s12
	s_ashr_i32 s3, s2, 31
	s_lshl_b64 s[8:9], s[2:3], 9
	v_lshl_add_u64 v[72:73], v[8:9], 0, s[8:9]
	global_load_dwordx2 v[52:53], v[72:73], off
	s_mov_b64 s[8:9], 0x400000
	v_lshl_add_u64 v[72:73], v[72:73], 0, s[8:9]
	global_load_dwordx2 v[60:61], v[72:73], off
	s_add_i32 s2, s2, s6
	s_ashr_i32 s3, s2, 31
	s_lshl_b64 s[8:9], s[2:3], 9
	v_lshl_add_u64 v[72:73], v[8:9], 0, s[8:9]
	global_load_dwordx2 v[54:55], v[72:73], off
	s_mov_b64 s[8:9], 0x400000
	v_lshl_add_u64 v[72:73], v[72:73], 0, s[8:9]
	global_load_dwordx2 v[62:63], v[72:73], off
	s_add_i32 s2, s2, s6
	s_ashr_i32 s3, s2, 31
	s_lshl_b64 s[8:9], s[2:3], 9
	v_lshl_add_u64 v[72:73], v[8:9], 0, s[8:9]
	global_load_dwordx2 v[56:57], v[72:73], off
	s_mov_b64 s[8:9], 0x400000
	v_lshl_add_u64 v[72:73], v[72:73], 0, s[8:9]
	global_load_dwordx2 v[64:65], v[72:73], off
	s_add_i32 s2, s2, s6
	s_ashr_i32 s3, s2, 31
	s_lshl_b64 s[8:9], s[2:3], 9
	v_lshl_add_u64 v[72:73], v[8:9], 0, s[8:9]
	global_load_dwordx2 v[58:59], v[72:73], off
	s_mov_b64 s[8:9], 0x400000
	v_lshl_add_u64 v[72:73], v[72:73], 0, s[8:9]
	global_load_dwordx2 v[66:67], v[72:73], off
	s_add_i32 s2, s2, s6
	global_load_dwordx4 v[68:71], v[10:11], off
	s_waitcnt vmcnt(0)
	s_branch .LBB0_586
.LBB0_585:
	s_and_b32 s2, s12, 0x3ff
	s_cmpk_lg_i32 s2, 0x3ff
	v_cvt_pk_bf16_f32 v16, v17, s0
	s_cselect_b64 vcc, -1, 0
	s_add_i32 s12, s12, s6
	v_cndmask_b32_e32 v16, 0, v16, vcc
	v_lshl_add_u64 v[12:13], v[12:13], 4, v[14:15]
	s_cmpk_lt_i32 s12, 0x1000
	global_store_short v[12:13], v16, off
	s_cbranch_scc0 .LBB0_592
	s_branch .Lc2_st
; __device__ __forceinline__ unsigned cvt_pk_bf16(float lo, float hi) { f32x2_t v = {lo, hi}; bf16x2_t b = __builtin_convertvector(v, bf16x2_t); return __builtin_bit_cast(unsigned, b); }
; __device__ __forceinline__ float bf_lo(unsigned u) { return __uint_as_float(u << 16); }
; __device__ __forceinline__ float bf_hi(unsigned u) { return __uint_as_float(u & 0xffff0000u); }
; __device__ __forceinline__ float gelu_tanh(float x) { const float u = 0.7978845608f * (x + 0.044715f * x * x * x); return x * rcpf_(1.f + ex2(-2.88539008f * u)); }
; __device__ __forceinline__ int pi32(int r) { return (r & 0x13) | ((r & 4) << 1) | ((r & 8) >> 1); }
; __device__ __forceinline__ void cmp_stage2(const Ctx& C, int l) {
;     ...
;     for (int row = wi * NWAVES + C.wave; row < 4096; row += nwg2 * NWAVES) {
;         asm volatile("" ::: "memory");
;         const u32x2 hv = *((const u32x2*)(hid + (size_t)row * 256) + C.lane), hw = *((const u32x2*)(hid + (size_t)(row + 8192) * 256) + C.lane);
;         const f32x4 cbv = *((const f32x4*)cbias + C.lane);
;         const float h0 = gelu_tanh(bf_lo(hv.x) + bf_lo(hw.x) + cbv.x), h1 = gelu_tanh(bf_hi(hv.x) + bf_hi(hw.x) + cbv.y), h2 = gelu_tanh(bf_lo(hv.y) + bf_lo(hw.y) + cbv.z), h3 = gelu_tanh(bf_hi(hv.y) + bf_hi(hw.y) + cbv.w);
;         float acc = 0.f;
; #pragma unroll 4
;         for (int k = 0; k < 64; ++k) {
;             const float a0 = __int_as_float(__builtin_amdgcn_readlane(__float_as_int(h0), k)), a1 = __int_as_float(__builtin_amdgcn_readlane(__float_as_int(h1), k));
;             const float a2 = __int_as_float(__builtin_amdgcn_readlane(__float_as_int(h2), k)), a3 = __int_as_float(__builtin_amdgcn_readlane(__float_as_int(h3), k));
;             acc += a0 * ws2[(4 * k + 0) * 64 + d]; acc += a1 * ws2[(4 * k + 1) * 64 + d]; acc += a2 * ws2[(4 * k + 2) * 64 + d]; acc += a3 * ws2[(4 * k + 3) * 64 + d];
;         }
;         const int bg = row >> 10, n = row & 1023;
;         if (n == 1023) acc = 0.f;
;         const bf16_t o = (bf16_t)(cvt_pk_bf16(acc, 0.f) & 0xffffu);
;         if (kv == 0) ko[((size_t)((bg * 32 + (n >> 5)) * 4 + (d >> 4)) * 64 + pi32(n & 31) + 32 * ((d >> 3) & 1)) * 8 + (d & 7)] = o;
;         else vo[((size_t)((bg * 64 + (n >> 4)) * 2 + (d >> 5)) * 64 + (d & 31) + 32 * ((n >> 3) & 1)) * 8 + (n & 7)] = o;
.LBB0_586:
	s_ashr_i32 s13, s12, 31
	s_lshl_b64 s[2:3], s[12:13], 9
	v_lshl_add_u64 v[12:13], v[8:9], 0, s[2:3]
	v_mov_b32_e32 v18, v52
	v_mov_b32_e32 v19, v53
	v_add_co_u32_e32 v12, vcc, 0x400000, v12
	s_mov_b32 s2, 0
	s_nop 0
	v_addc_co_u32_e32 v13, vcc, 0, v13, vcc
	v_mov_b32_e32 v20, v60
	v_mov_b32_e32 v21, v61
	s_nop 0
	v_mov_b32_e32 v12, v68
	v_mov_b32_e32 v13, v69
	v_mov_b32_e32 v14, v70
	v_mov_b32_e32 v15, v71
	v_mov_b32_e32 v52, v54
	v_mov_b32_e32 v53, v55
	v_mov_b32_e32 v54, v56
	v_mov_b32_e32 v55, v57
	v_mov_b32_e32 v56, v58
	v_mov_b32_e32 v57, v59
	v_mov_b32_e32 v60, v62
	v_mov_b32_e32 v61, v63
	v_mov_b32_e32 v62, v64
	v_mov_b32_e32 v63, v65
	v_mov_b32_e32 v64, v66
	v_mov_b32_e32 v65, v67
	v_mov_b32_e32 v17, 0
	s_waitcnt vmcnt(2)
	v_lshlrev_b32_e32 v16, 16, v18
	v_and_b32_e32 v18, 0xffff0000, v18
	v_lshlrev_b32_e32 v22, 16, v19
	v_and_b32_e32 v19, 0xffff0000, v19
	s_waitcnt vmcnt(1)
	v_lshlrev_b32_e32 v23, 16, v20
	v_and_b32_e32 v20, 0xffff0000, v20
	v_lshlrev_b32_e32 v24, 16, v21
	v_and_b32_e32 v21, 0xffff0000, v21
	v_add_f32_e32 v16, v16, v23
	v_add_f32_e32 v18, v18, v20
	v_add_f32_e32 v20, v22, v24
	v_add_f32_e32 v19, v19, v21
	s_waitcnt vmcnt(0)
	v_add_f32_e32 v12, v12, v16
	v_add_f32_e32 v13, v13, v18
	v_add_f32_e32 v14, v14, v20
	v_add_f32_e32 v15, v15, v19
	v_mul_f32_e32 v16, 0x3d372713, v12
	v_mul_f32_e32 v18, 0x3d372713, v13
	v_mul_f32_e32 v19, 0x3d372713, v14
	v_mul_f32_e32 v20, 0x3d372713, v15
	v_mul_f32_e32 v16, v12, v16
	v_mul_f32_e32 v18, v13, v18
	v_mul_f32_e32 v19, v14, v19
	v_mul_f32_e32 v20, v15, v20
	v_fma_f32 v16, v12, v16, v12
	v_fma_f32 v18, v13, v18, v13
	v_fma_f32 v19, v14, v19, v14
	v_fma_f32 v20, v15, v20, v15
	v_mul_f32_e32 v16, 0x3f4c422a, v16
	v_mul_f32_e32 v18, 0x3f4c422a, v18
	v_mul_f32_e32 v19, 0x3f4c422a, v19
	v_mul_f32_e32 v20, 0x3f4c422a, v20
	v_mul_f32_e32 v16, 0xc038aa3b, v16
	v_mul_f32_e32 v18, 0xc038aa3b, v18
	v_mul_f32_e32 v19, 0xc038aa3b, v19
	v_mul_f32_e32 v20, 0xc038aa3b, v20
	v_exp_f32_e32 v16, v16
	v_exp_f32_e32 v18, v18
	v_exp_f32_e32 v19, v19
	v_exp_f32_e32 v20, v20
	v_add_f32_e32 v16, 1.0, v16
	v_add_f32_e32 v18, 1.0, v18
	v_add_f32_e32 v19, 1.0, v19
	v_add_f32_e32 v20, 1.0, v20
	v_rcp_f32_e32 v16, v16
	v_rcp_f32_e32 v18, v18
	v_rcp_f32_e32 v19, v19
	v_rcp_f32_e32 v20, v20
	v_mul_f32_e32 v12, v12, v16
	v_mul_f32_e32 v13, v13, v18
	v_mul_f32_e32 v14, v14, v19
	v_mul_f32_e32 v15, v15, v20
	ds_write_b128 v30, v[12:15]
	v_add_u32_e32 v30, 0x400, v30
	s_add_i32 s12, s12, s6
	s_cmpk_lt_i32 s12, 0x1000
	s_cbranch_scc1 .LBB0_586
	v_mov_b32_e32 v16, v0
	v_mov_b32_e32 v32, 0
	v_mov_b32_e32 v33, 0
	v_mov_b32_e32 v34, 0
	v_mov_b32_e32 v35, 0
	s_waitcnt lgkmcnt(0)
	ds_read_b128 v[36:39], v31
	ds_read2st64_b32 v[44:45], v16 offset1:1
	ds_read2st64_b32 v[46:47], v16 offset0:2 offset1:3
	s_mov_b32 s2, 0
.Lc2_k:
	ds_read_b128 v[40:43], v31 offset:16
	ds_read2st64_b32 v[48:49], v16 offset0:4 offset1:5
	ds_read2st64_b32 v[50:51], v16 offset0:6 offset1:7
	s_waitcnt lgkmcnt(3)
	v_mfma_f32_4x4x1_16b_f32 v[32:35], v36, v44, v[32:35]
	s_nop 1
	v_mfma_f32_4x4x1_16b_f32 v[32:35], v37, v45, v[32:35]
	s_nop 1
	v_mfma_f32_4x4x1_16b_f32 v[32:35], v38, v46, v[32:35]
	s_nop 1
	v_mfma_f32_4x4x1_16b_f32 v[32:35], v39, v47, v[32:35]
	ds_read_b128 v[36:39], v31 offset:32
	ds_read2st64_b32 v[44:45], v16 offset0:8 offset1:9
	ds_read2st64_b32 v[46:47], v16 offset0:10 offset1:11
	s_waitcnt lgkmcnt(3)
	v_mfma_f32_4x4x1_16b_f32 v[32:35], v40, v48, v[32:35]
	s_nop 1
	v_mfma_f32_4x4x1_16b_f32 v[32:35], v41, v49, v[32:35]
	s_nop 1
	v_mfma_f32_4x4x1_16b_f32 v[32:35], v42, v50, v[32:35]
	s_nop 1
	v_mfma_f32_4x4x1_16b_f32 v[32:35], v43, v51, v[32:35]
	v_add_u32_e32 v31, 32, v31
	v_add_u32_e32 v16, 0x800, v16
	s_add_i32 s2, s2, 2
	s_cmp_eq_u32 s2, 64
	s_cbranch_scc0 .Lc2_k
	s_waitcnt lgkmcnt(0)
	s_nop 3
	s_mov_b32 s12, s100
.Lc2_st:
	v_mov_b32_e32 v17, v32
	v_mov_b32_e32 v32, v33
	v_mov_b32_e32 v33, v34
	v_mov_b32_e32 v34, v35
	s_ashr_i32 s2, s12, 3
	s_and_b32 s8, s2, 0xffffff80
	s_lshr_b32 s9, s12, 3
	s_mov_b64 s[2:3], -1
	s_and_b64 vcc, exec, s[4:5]
	s_cbranch_vccz .LBB0_590
	s_and_b32 s2, s9, 0x7e
	v_or_b32_e32 v12, s2, v3
	v_or_b32_e32 v12, s8, v12
	v_ashrrev_i32_e32 v13, 31, v12
	v_lshlrev_b64 v[12:13], 6, v[12:13]
	v_or_b32_e32 v12, v12, v2
	s_lshl_b32 s2, s12, 2
	v_and_or_b32 v12, s2, 32, v12
	s_mov_b64 s[2:3], 0

; __global__ void __launch_bounds__(NWAVES * 64, 2) fwd_kernel(Args args) {
;     extern __shared__ __attribute__((aligned(16))) unsigned char lds_raw[];
	.amdhsa_kernel _Z10fwd_kernel4Args
		.amdhsa_group_segment_fixed_size 0
		.amdhsa_private_segment_fixed_size 0
		.amdhsa_kernarg_size 512
		.amdhsa_user_sgpr_count 2
		.amdhsa_user_sgpr_dispatch_ptr 0
		.amdhsa_user_sgpr_queue_ptr 0
		.amdhsa_user_sgpr_kernarg_segment_ptr 1
		.amdhsa_user_sgpr_dispatch_id 0
		.amdhsa_user_sgpr_kernarg_preload_length 0
		.amdhsa_user_sgpr_kernarg_preload_offset 0
		.amdhsa_user_sgpr_private_segment_size 0
		.amdhsa_uses_dynamic_stack 0
		.amdhsa_enable_private_segment 0
		.amdhsa_system_sgpr_workgroup_id_x 1
		.amdhsa_system_sgpr_workgroup_id_y 0
		.amdhsa_system_sgpr_workgroup_id_z 0
		.amdhsa_system_sgpr_workgroup_info 0
		.amdhsa_system_vgpr_workitem_id 2
		.amdhsa_next_free_vgpr 256
		.amdhsa_next_free_sgpr 102
		.amdhsa_accum_offset 256
		.amdhsa_reserve_vcc 1
		.amdhsa_float_round_mode_32 0
		.amdhsa_float_round_mode_16_64 0
		.amdhsa_float_denorm_mode_32 3
		.amdhsa_float_denorm_mode_16_64 3
		.amdhsa_dx10_clamp 1
		.amdhsa_ieee_mode 1
		.amdhsa_fp16_overflow 0
		.amdhsa_tg_split 0
		.amdhsa_exception_fp_ieee_invalid_op 0
		.amdhsa_exception_fp_denorm_src 0
		.amdhsa_exception_fp_ieee_div_zero 0
		.amdhsa_exception_fp_ieee_overflow 0
		.amdhsa_exception_fp_ieee_underflow 0
		.amdhsa_exception_fp_ieee_inexact 0
		.amdhsa_exception_int_div_zero 0
	.end_amdhsa_kernel

; __global__ void __launch_bounds__(NWAVES * 64, 2) fwd_kernel(Args args) {
;     extern __shared__ __attribute__((aligned(16))) unsigned char lds_raw[];
amdhsa.kernels:
  - .agpr_count:     0
    .args:
      - .offset:         0
        .size:           256
        .value_kind:     by_value
      - .offset:         256
        .size:           4
        .value_kind:     hidden_block_count_x
      - .offset:         260
        .size:           4
        .value_kind:     hidden_block_count_y
      - .offset:         264
        .size:           4
        .value_kind:     hidden_block_count_z
      - .offset:         268
        .size:           2
        .value_kind:     hidden_group_size_x
      - .offset:         270
        .size:           2
        .value_kind:     hidden_group_size_y
      - .offset:         272
        .size:           2
        .value_kind:     hidden_group_size_z
      - .offset:         274
        .size:           2
        .value_kind:     hidden_remainder_x
      - .offset:         276
        .size:           2
        .value_kind:     hidden_remainder_y
      - .offset:         278
        .size:           2
        .value_kind:     hidden_remainder_z
      - .offset:         296
        .size:           8
        .value_kind:     hidden_global_offset_x
      - .offset:         304
        .size:           8
        .value_kind:     hidden_global_offset_y
      - .offset:         312
        .size:           8
        .value_kind:     hidden_global_offset_z
      - .offset:         320
        .size:           2
        .value_kind:     hidden_grid_dims
      - .offset:         344
        .size:           8
        .value_kind:     hidden_multigrid_sync_arg
      - .offset:         376
        .size:           4
        .value_kind:     hidden_dynamic_lds_size
    .group_segment_fixed_size: 0
    .kernarg_segment_align: 8
    .kernarg_segment_size: 512
    .language:       OpenCL C
    .language_version:
      - 2
      - 0
    .max_flat_workgroup_size: 512
    .name:           _Z10fwd_kernel4Args
    .private_segment_fixed_size: 0
    .sgpr_count:     108
    .sgpr_spill_count: 151
    .symbol:         _Z10fwd_kernel4Args.kd
    .uniform_work_group_size: 1
    .uses_dynamic_stack: false
    .vgpr_count:     256
    .vgpr_spill_count: 0
    .wavefront_size: 64
